# P5 epilogue: pass-1 residual loads in a 12-deep register ring with counted vmcnt; pass-2 rstd preloaded from LDS once
# baseline (speedup 1.0000x reference)
; #define LAS __attribute__((address_space(3)))
; __device__ __forceinline__ unsigned cvt_pk_bf16(float lo, float hi) { unsigned r; asm volatile("v_cvt_pk_bf16_f32 %0, %1, %2" : "=v"(r) : "v"(lo), "v"(hi)); return r; }
;     __device__ __forceinline__ void fused(f32x4 (&acc)[2][2][4][2], const Unit& u, int wr, int wc, int fr, int fq, LAS unsigned char* lds, int wid, int lane) const {
;     ...
;         const LAS float* S = (const LAS float*)(lds + 4096);
; #pragma unroll
;         for (int bj = 0; bj < 2; ++bj)
; #pragma unroll
;             for (int n = 0; n < 2; ++n) { const int co = bj * HALF + n * 16;
;                 const f32x4 gg = *(const f32x4*)(g + col0 + co), sh = *(const f32x4*)(modb + sh_off + co), sc = *(const f32x4*)(modb + sc_off + co);
;                 const f32x4 mul = gg * (1.0f + sc);
; #pragma unroll
;                 for (int ai = 0; ai < 2; ++ai)
; #pragma unroll
;                     for (int m = 0; m < 4; ++m) { const int r = ai * HALF + wr * 64 + m * 16 + fr; const float rstd = S[r];
;                         const f32x4 h = (acc[ai][bj][m][n] * rstd) * mul + sh;
;                         u32x2 w; w.x = cvt_pk_bf16(h[0], h[1]); w.y = cvt_pk_bf16(h[2], h[3]);
;                         *(u32x2*)(hn + (size_t)(u.pm * BM + r) * DM + col0 + co) = w; } }
.LBB0_615:
	s_or_b64 exec, exec, s[6:7]
	v_add_co_u32_e32 v130, vcc, 0x3000, v146
	s_mov_b64 s[0:1], vcc
	v_add_co_u32_e32 v132, vcc, 0x4000, v146
	s_waitcnt lgkmcnt(0)
	s_barrier
	s_nop 0
	v_addc_co_u32_e32 v133, vcc, 0, v147, vcc
	v_lshl_add_u64 v[128:129], v[144:145], 2, s[18:19]
	global_load_dwordx4 v[148:151], v[132:133], off
	global_load_dwordx4 v[154:157], v[128:129], off
	v_addc_co_u32_e64 v131, vcc, 0, v147, s[0:1]
	global_load_dwordx4 v[0:3], v[130:131], off
	v_lshl_add_u32 v136, v152, 2, 0
	v_lshlrev_b64 v[134:135], 1, v[144:145]
	ds_read_b32 v176, v136 offset:4096
	ds_read_b32 v178, v136 offset:4160
	ds_read_b32 v180, v136 offset:4224
	ds_read_b32 v182, v136 offset:4288
	ds_read_b32 v184, v136 offset:4608
	ds_read_b32 v186, v136 offset:4672
	ds_read_b32 v188, v136 offset:4736
	ds_read_b32 v190, v136 offset:4800
	v_add_u32_e32 v138, s10, v152
	s_add_u32 s0, s34, 0x2f00000
	v_ashrrev_i32_e32 v139, 31, v138
	s_addc_u32 s1, s35, 0
	s_waitcnt lgkmcnt(0)
	v_pk_mul_f32 v[124:125], v[124:125], v[176:177] op_sel_hi:[1,0]
	v_pk_mul_f32 v[126:127], v[126:127], v[176:177] op_sel_hi:[1,0]
	v_add_u32_e32 v146, 16, v138
	v_add_u32_e32 v152, 32, v138
	v_add_u32_e32 v158, 48, v138
	v_add_u32_e32 v160, 0x80, v138
	v_add_u32_e32 v162, 0x90, v138
	v_add_u32_e32 v164, 0xa0, v138
	v_add_u32_e32 v166, 0xb0, v138
	v_lshlrev_b64 v[138:139], 11, v[138:139]
	v_lshl_add_u64 v[138:139], s[0:1], 0, v[138:139]
	v_ashrrev_i32_e32 v147, 31, v146
	v_lshlrev_b64 v[146:147], 11, v[146:147]
	v_ashrrev_i32_e32 v153, 31, v152
	v_lshlrev_b64 v[152:153], 11, v[152:153]
	v_ashrrev_i32_e32 v159, 31, v158
	v_ashrrev_i32_e32 v161, 31, v160
	v_ashrrev_i32_e32 v163, 31, v162
	v_ashrrev_i32_e32 v165, 31, v164
	v_ashrrev_i32_e32 v167, 31, v166
	s_waitcnt vmcnt(2)
	v_pk_add_f32 v[144:145], v[150:151], 1.0 op_sel_hi:[1,0]
	v_pk_add_f32 v[148:149], v[148:149], 1.0 op_sel_hi:[1,0]
	s_waitcnt vmcnt(1)
	v_pk_mul_f32 v[144:145], v[156:157], v[144:145]
	v_pk_mul_f32 v[148:149], v[154:155], v[148:149]
	s_waitcnt vmcnt(0)
	v_pk_fma_f32 v[126:127], v[144:145], v[126:127], v[2:3]
	v_pk_fma_f32 v[124:125], v[148:149], v[124:125], v[0:1]
	v_lshlrev_b64 v[154:155], 11, v[158:159]
	v_cvt_pk_bf16_f32 v150, v124, v125
	v_cvt_pk_bf16_f32 v151, v126, v127
	v_lshl_add_u64 v[124:125], v[138:139], 0, v[134:135]
	global_store_dwordx2 v[124:125], v[150:151], off
	v_lshlrev_b64 v[138:139], 11, v[160:161]
	s_waitcnt lgkmcnt(0)
	v_pk_mul_f32 v[114:115], v[114:115], v[178:179] op_sel_hi:[1,0]
	v_pk_mul_f32 v[112:113], v[112:113], v[178:179] op_sel_hi:[1,0]
	v_pk_fma_f32 v[114:115], v[144:145], v[114:115], v[2:3]
	v_pk_fma_f32 v[112:113], v[148:149], v[112:113], v[0:1]
	s_nop 0
	v_cvt_pk_bf16_f32 v126, v112, v113
	v_cvt_pk_bf16_f32 v127, v114, v115
	v_lshl_add_u64 v[112:113], s[0:1], 0, v[146:147]
	v_lshl_add_u64 v[112:113], v[112:113], 0, v[134:135]
	global_store_dwordx2 v[112:113], v[126:127], off
	v_lshlrev_b64 v[126:127], 11, v[162:163]
	s_waitcnt lgkmcnt(0)
	v_pk_mul_f32 v[98:99], v[98:99], v[180:181] op_sel_hi:[1,0]
	v_pk_mul_f32 v[96:97], v[96:97], v[180:181] op_sel_hi:[1,0]
	v_pk_fma_f32 v[98:99], v[144:145], v[98:99], v[2:3]
	v_pk_fma_f32 v[96:97], v[148:149], v[96:97], v[0:1]
	s_nop 0
	v_cvt_pk_bf16_f32 v114, v96, v97
	v_cvt_pk_bf16_f32 v115, v98, v99
	v_lshl_add_u64 v[96:97], s[0:1], 0, v[152:153]
	v_lshl_add_u64 v[96:97], v[96:97], 0, v[134:135]
	global_store_dwordx2 v[96:97], v[114:115], off
	v_lshlrev_b64 v[114:115], 11, v[164:165]
	s_waitcnt lgkmcnt(0)
	v_pk_mul_f32 v[82:83], v[82:83], v[182:183] op_sel_hi:[1,0]
	v_pk_mul_f32 v[80:81], v[80:81], v[182:183] op_sel_hi:[1,0]
	v_pk_fma_f32 v[82:83], v[144:145], v[82:83], v[2:3]
	v_pk_fma_f32 v[80:81], v[148:149], v[80:81], v[0:1]
	s_nop 0
	v_cvt_pk_bf16_f32 v98, v80, v81
	v_cvt_pk_bf16_f32 v99, v82, v83
	v_lshl_add_u64 v[80:81], s[0:1], 0, v[154:155]
	v_lshl_add_u64 v[80:81], v[80:81], 0, v[134:135]
	global_store_dwordx2 v[80:81], v[98:99], off
	v_lshlrev_b64 v[98:99], 11, v[166:167]
	s_waitcnt lgkmcnt(0)
	v_pk_mul_f32 v[62:63], v[62:63], v[184:185] op_sel_hi:[1,0]
	v_pk_mul_f32 v[60:61], v[60:61], v[184:185] op_sel_hi:[1,0]
	v_pk_fma_f32 v[62:63], v[144:145], v[62:63], v[2:3]
	v_pk_fma_f32 v[60:61], v[148:149], v[60:61], v[0:1]
	s_nop 0
	v_cvt_pk_bf16_f32 v82, v60, v61
	v_cvt_pk_bf16_f32 v83, v62, v63
	v_lshl_add_u64 v[60:61], s[0:1], 0, v[138:139]
	v_lshl_add_u64 v[60:61], v[60:61], 0, v[134:135]
	global_store_dwordx2 v[60:61], v[82:83], off
	v_lshl_add_u64 v[82:83], s[0:1], 0, v[114:115]
	s_waitcnt lgkmcnt(0)
	v_pk_mul_f32 v[50:51], v[50:51], v[186:187] op_sel_hi:[1,0]
	v_pk_mul_f32 v[48:49], v[48:49], v[186:187] op_sel_hi:[1,0]
	v_pk_fma_f32 v[50:51], v[144:145], v[50:51], v[2:3]
	v_pk_fma_f32 v[48:49], v[148:149], v[48:49], v[0:1]
	s_nop 0
	v_cvt_pk_bf16_f32 v62, v48, v49
	v_cvt_pk_bf16_f32 v63, v50, v51
	v_lshl_add_u64 v[48:49], s[0:1], 0, v[126:127]
	v_lshl_add_u64 v[48:49], v[48:49], 0, v[134:135]
	global_store_dwordx2 v[48:49], v[62:63], off
	s_waitcnt lgkmcnt(0)
	v_pk_mul_f32 v[32:33], v[32:33], v[188:189] op_sel_hi:[1,0]
	v_pk_mul_f32 v[34:35], v[34:35], v[188:189] op_sel_hi:[1,0]
	v_pk_fma_f32 v[32:33], v[148:149], v[32:33], v[0:1]
	v_pk_fma_f32 v[34:35], v[144:145], v[34:35], v[2:3]
	v_cvt_pk_bf16_f32 v50, v32, v33
	v_lshl_add_u64 v[32:33], s[0:1], 0, v[98:99]
	v_cvt_pk_bf16_f32 v51, v34, v35
	v_lshl_add_u64 v[34:35], v[82:83], 0, v[134:135]
	global_store_dwordx2 v[34:35], v[50:51], off
	v_lshl_add_u64 v[32:33], v[32:33], 0, v[134:135]
	s_waitcnt lgkmcnt(0)
; #define LAS __attribute__((address_space(3)))
; __device__ __forceinline__ unsigned cvt_pk_bf16(float lo, float hi) { unsigned r; asm volatile("v_cvt_pk_bf16_f32 %0, %1, %2" : "=v"(r) : "v"(lo), "v"(hi)); return r; }
;     __device__ __forceinline__ void fused(f32x4 (&acc)[2][2][4][2], const Unit& u, int wr, int wc, int fr, int fq, LAS unsigned char* lds, int wid, int lane) const {
;     ...
;         const LAS float* S = (const LAS float*)(lds + 4096);
; #pragma unroll
;         for (int bj = 0; bj < 2; ++bj)
; #pragma unroll
;             for (int n = 0; n < 2; ++n) { const int co = bj * HALF + n * 16;
;                 const f32x4 gg = *(const f32x4*)(g + col0 + co), sh = *(const f32x4*)(modb + sh_off + co), sc = *(const f32x4*)(modb + sc_off + co);
;                 const f32x4 mul = gg * (1.0f + sc);
; #pragma unroll
;                 for (int ai = 0; ai < 2; ++ai)
; #pragma unroll
;                     for (int m = 0; m < 4; ++m) { const int r = ai * HALF + wr * 64 + m * 16 + fr; const float rstd = S[r];
;                         const f32x4 h = (acc[ai][bj][m][n] * rstd) * mul + sh;
;                         u32x2 w; w.x = cvt_pk_bf16(h[0], h[1]); w.y = cvt_pk_bf16(h[2], h[3]);
;                         *(u32x2*)(hn + (size_t)(u.pm * BM + r) * DM + col0 + co) = w; } }
	v_pk_mul_f32 v[50:51], v[140:141], v[190:191] op_sel_hi:[1,0]
	v_pk_mul_f32 v[62:63], v[142:143], v[190:191] op_sel_hi:[1,0]
	v_pk_fma_f32 v[0:1], v[148:149], v[50:51], v[0:1]
	v_pk_fma_f32 v[2:3], v[144:145], v[62:63], v[2:3]
	v_cvt_pk_bf16_f32 v0, v0, v1
	s_nop 0
	v_cvt_pk_bf16_f32 v1, v2, v3
	global_store_dwordx2 v[32:33], v[0:1], off
	global_load_dwordx4 v[0:3], v[132:133], off offset:64
	s_nop 0
	global_load_dwordx4 v[138:141], v[128:129], off offset:64
	global_load_dwordx4 v[142:145], v[130:131], off offset:64
	s_waitcnt lgkmcnt(0)
	v_pk_mul_f32 v[62:63], v[120:121], v[176:177] op_sel_hi:[1,0]
	v_pk_mul_f32 v[50:51], v[122:123], v[176:177] op_sel_hi:[1,0]
	s_waitcnt vmcnt(2)
	v_pk_add_f32 v[2:3], v[2:3], 1.0 op_sel_hi:[1,0]
	v_pk_add_f32 v[0:1], v[0:1], 1.0 op_sel_hi:[1,0]
	s_waitcnt vmcnt(1)
	v_pk_mul_f32 v[2:3], v[140:141], v[2:3]
	v_pk_mul_f32 v[0:1], v[138:139], v[0:1]
	s_waitcnt vmcnt(0)
	v_pk_fma_f32 v[50:51], v[2:3], v[50:51], v[144:145]
	v_pk_fma_f32 v[62:63], v[0:1], v[62:63], v[142:143]
	s_nop 0
	v_cvt_pk_bf16_f32 v62, v62, v63
	v_cvt_pk_bf16_f32 v63, v50, v51
	global_store_dwordx2 v[124:125], v[62:63], off offset:32
	s_waitcnt lgkmcnt(0)
	v_pk_mul_f32 v[62:63], v[104:105], v[178:179] op_sel_hi:[1,0]
	v_pk_mul_f32 v[50:51], v[106:107], v[178:179] op_sel_hi:[1,0]
	v_pk_fma_f32 v[62:63], v[0:1], v[62:63], v[142:143]
	v_pk_fma_f32 v[50:51], v[2:3], v[50:51], v[144:145]
	v_cvt_pk_bf16_f32 v62, v62, v63
	s_nop 0
	v_cvt_pk_bf16_f32 v63, v50, v51
	global_store_dwordx2 v[112:113], v[62:63], off offset:32
	s_waitcnt lgkmcnt(0)
	v_pk_mul_f32 v[62:63], v[88:89], v[180:181] op_sel_hi:[1,0]
	v_pk_mul_f32 v[50:51], v[90:91], v[180:181] op_sel_hi:[1,0]
	v_pk_fma_f32 v[62:63], v[0:1], v[62:63], v[142:143]
	v_pk_fma_f32 v[50:51], v[2:3], v[50:51], v[144:145]
	v_cvt_pk_bf16_f32 v62, v62, v63
	s_nop 0
	v_cvt_pk_bf16_f32 v63, v50, v51
	global_store_dwordx2 v[96:97], v[62:63], off offset:32
	s_waitcnt lgkmcnt(0)
	v_pk_mul_f32 v[62:63], v[72:73], v[182:183] op_sel_hi:[1,0]
	v_pk_mul_f32 v[50:51], v[74:75], v[182:183] op_sel_hi:[1,0]
	v_pk_fma_f32 v[62:63], v[0:1], v[62:63], v[142:143]
	v_pk_fma_f32 v[50:51], v[2:3], v[50:51], v[144:145]
	v_cvt_pk_bf16_f32 v62, v62, v63
	s_nop 0
	v_cvt_pk_bf16_f32 v63, v50, v51
	global_store_dwordx2 v[80:81], v[62:63], off offset:32
	s_waitcnt lgkmcnt(0)
	v_pk_mul_f32 v[56:57], v[56:57], v[184:185] op_sel_hi:[1,0]
	v_pk_mul_f32 v[50:51], v[58:59], v[184:185] op_sel_hi:[1,0]
	v_pk_fma_f32 v[56:57], v[0:1], v[56:57], v[142:143]
	v_pk_fma_f32 v[50:51], v[2:3], v[50:51], v[144:145]
	v_cvt_pk_bf16_f32 v56, v56, v57
	s_nop 0
	v_cvt_pk_bf16_f32 v57, v50, v51
	global_store_dwordx2 v[60:61], v[56:57], off offset:32
	s_waitcnt lgkmcnt(0)
	v_pk_mul_f32 v[40:41], v[40:41], v[186:187] op_sel_hi:[1,0]
	v_pk_mul_f32 v[42:43], v[42:43], v[186:187] op_sel_hi:[1,0]
	v_pk_fma_f32 v[40:41], v[0:1], v[40:41], v[142:143]
	v_pk_fma_f32 v[42:43], v[2:3], v[42:43], v[144:145]
	v_cvt_pk_bf16_f32 v40, v40, v41
	s_nop 0
	v_cvt_pk_bf16_f32 v41, v42, v43
	global_store_dwordx2 v[48:49], v[40:41], off offset:32
	s_waitcnt lgkmcnt(0)
	v_pk_mul_f32 v[24:25], v[24:25], v[188:189] op_sel_hi:[1,0]
	v_pk_mul_f32 v[26:27], v[26:27], v[188:189] op_sel_hi:[1,0]
	v_pk_fma_f32 v[24:25], v[0:1], v[24:25], v[142:143]
	v_pk_fma_f32 v[26:27], v[2:3], v[26:27], v[144:145]
	v_cvt_pk_bf16_f32 v24, v24, v25
	s_nop 0
	v_cvt_pk_bf16_f32 v25, v26, v27
	global_store_dwordx2 v[34:35], v[24:25], off offset:32
	s_waitcnt lgkmcnt(0)
	v_pk_mul_f32 v[18:19], v[18:19], v[190:191] op_sel_hi:[1,0]
	v_pk_mul_f32 v[16:17], v[16:17], v[190:191] op_sel_hi:[1,0]
	v_pk_fma_f32 v[0:1], v[0:1], v[18:19], v[142:143]
	v_pk_fma_f32 v[2:3], v[2:3], v[16:17], v[144:145]
	v_cvt_pk_bf16_f32 v0, v0, v1
	s_nop 0
	v_cvt_pk_bf16_f32 v1, v2, v3
	global_store_dwordx2 v[32:33], v[0:1], off offset:32
	global_load_dwordx4 v[0:3], v[132:133], off offset:512
	s_nop 0
	global_load_dwordx4 v[16:19], v[128:129], off offset:512
	global_load_dwordx4 v[24:27], v[130:131], off offset:512
	s_waitcnt lgkmcnt(0)
	v_pk_mul_f32 v[42:43], v[116:117], v[176:177] op_sel_hi:[1,0]
	v_pk_mul_f32 v[40:41], v[118:119], v[176:177] op_sel_hi:[1,0]
	s_waitcnt vmcnt(2)
	v_pk_add_f32 v[2:3], v[2:3], 1.0 op_sel_hi:[1,0]
	v_pk_add_f32 v[0:1], v[0:1], 1.0 op_sel_hi:[1,0]
	s_waitcnt vmcnt(1)
	v_pk_mul_f32 v[2:3], v[18:19], v[2:3]
	v_pk_mul_f32 v[0:1], v[16:17], v[0:1]
	s_waitcnt vmcnt(0)
	v_pk_fma_f32 v[16:17], v[2:3], v[40:41], v[26:27]
	v_pk_fma_f32 v[18:19], v[0:1], v[42:43], v[24:25]
	s_nop 0
	v_cvt_pk_bf16_f32 v18, v18, v19
	v_cvt_pk_bf16_f32 v19, v16, v17
	global_store_dwordx2 v[124:125], v[18:19], off offset:256
	s_waitcnt lgkmcnt(0)
	v_pk_mul_f32 v[18:19], v[100:101], v[178:179] op_sel_hi:[1,0]
	v_pk_mul_f32 v[16:17], v[102:103], v[178:179] op_sel_hi:[1,0]
	v_pk_fma_f32 v[18:19], v[0:1], v[18:19], v[24:25]
	v_pk_fma_f32 v[16:17], v[2:3], v[16:17], v[26:27]
	v_cvt_pk_bf16_f32 v18, v18, v19
	s_nop 0
	v_cvt_pk_bf16_f32 v19, v16, v17
	global_store_dwordx2 v[112:113], v[18:19], off offset:256
	s_waitcnt lgkmcnt(0)
	v_pk_mul_f32 v[18:19], v[84:85], v[180:181] op_sel_hi:[1,0]
	v_pk_mul_f32 v[16:17], v[86:87], v[180:181] op_sel_hi:[1,0]
	v_pk_fma_f32 v[18:19], v[0:1], v[18:19], v[24:25]
	v_pk_fma_f32 v[16:17], v[2:3], v[16:17], v[26:27]
	v_cvt_pk_bf16_f32 v18, v18, v19
	s_nop 0
	v_cvt_pk_bf16_f32 v19, v16, v17
	global_store_dwordx2 v[96:97], v[18:19], off offset:256
	s_waitcnt lgkmcnt(0)
; #define LAS __attribute__((address_space(3)))
; __device__ __forceinline__ unsigned cvt_pk_bf16(float lo, float hi) { unsigned r; asm volatile("v_cvt_pk_bf16_f32 %0, %1, %2" : "=v"(r) : "v"(lo), "v"(hi)); return r; }
;     __device__ __forceinline__ void fused(f32x4 (&acc)[2][2][4][2], const Unit& u, int wr, int wc, int fr, int fq, LAS unsigned char* lds, int wid, int lane) const {
;     ...
;         const LAS float* S = (const LAS float*)(lds + 4096);
; #pragma unroll
;         for (int bj = 0; bj < 2; ++bj)
; #pragma unroll
;             for (int n = 0; n < 2; ++n) { const int co = bj * HALF + n * 16;
;                 const f32x4 gg = *(const f32x4*)(g + col0 + co), sh = *(const f32x4*)(modb + sh_off + co), sc = *(const f32x4*)(modb + sc_off + co);
;                 const f32x4 mul = gg * (1.0f + sc);
; #pragma unroll
;                 for (int ai = 0; ai < 2; ++ai)
; #pragma unroll
;                     for (int m = 0; m < 4; ++m) { const int r = ai * HALF + wr * 64 + m * 16 + fr; const float rstd = S[r];
;                         const f32x4 h = (acc[ai][bj][m][n] * rstd) * mul + sh;
;                         u32x2 w; w.x = cvt_pk_bf16(h[0], h[1]); w.y = cvt_pk_bf16(h[2], h[3]);
;                         *(u32x2*)(hn + (size_t)(u.pm * BM + r) * DM + col0 + co) = w; } }
	v_pk_mul_f32 v[18:19], v[68:69], v[182:183] op_sel_hi:[1,0]
	v_pk_mul_f32 v[16:17], v[70:71], v[182:183] op_sel_hi:[1,0]
	v_pk_fma_f32 v[18:19], v[0:1], v[18:19], v[24:25]
	v_pk_fma_f32 v[16:17], v[2:3], v[16:17], v[26:27]
	v_cvt_pk_bf16_f32 v18, v18, v19
	s_nop 0
	v_cvt_pk_bf16_f32 v19, v16, v17
	global_store_dwordx2 v[80:81], v[18:19], off offset:256
	s_waitcnt lgkmcnt(0)
	v_pk_mul_f32 v[18:19], v[52:53], v[184:185] op_sel_hi:[1,0]
	v_pk_mul_f32 v[16:17], v[54:55], v[184:185] op_sel_hi:[1,0]
	v_pk_fma_f32 v[18:19], v[0:1], v[18:19], v[24:25]
	v_pk_fma_f32 v[16:17], v[2:3], v[16:17], v[26:27]
	v_cvt_pk_bf16_f32 v18, v18, v19
	s_nop 0
	v_cvt_pk_bf16_f32 v19, v16, v17
	global_store_dwordx2 v[60:61], v[18:19], off offset:256
	s_waitcnt lgkmcnt(0)
	v_pk_mul_f32 v[18:19], v[36:37], v[186:187] op_sel_hi:[1,0]
	v_pk_mul_f32 v[16:17], v[38:39], v[186:187] op_sel_hi:[1,0]
	v_pk_fma_f32 v[18:19], v[0:1], v[18:19], v[24:25]
	v_pk_fma_f32 v[16:17], v[2:3], v[16:17], v[26:27]
	v_cvt_pk_bf16_f32 v18, v18, v19
	s_nop 0
	v_cvt_pk_bf16_f32 v19, v16, v17
	global_store_dwordx2 v[48:49], v[18:19], off offset:256
	s_waitcnt lgkmcnt(0)
	v_pk_mul_f32 v[18:19], v[20:21], v[188:189] op_sel_hi:[1,0]
	v_pk_mul_f32 v[16:17], v[22:23], v[188:189] op_sel_hi:[1,0]
	v_pk_fma_f32 v[18:19], v[0:1], v[18:19], v[24:25]
	v_pk_fma_f32 v[16:17], v[2:3], v[16:17], v[26:27]
	v_cvt_pk_bf16_f32 v18, v18, v19
	s_nop 0
	v_cvt_pk_bf16_f32 v19, v16, v17
	global_store_dwordx2 v[34:35], v[18:19], off offset:256
	s_waitcnt lgkmcnt(0)
	v_pk_mul_f32 v[10:11], v[10:11], v[190:191] op_sel_hi:[1,0]
	v_pk_mul_f32 v[8:9], v[8:9], v[190:191] op_sel_hi:[1,0]
	v_pk_fma_f32 v[0:1], v[0:1], v[10:11], v[24:25]
	v_pk_fma_f32 v[2:3], v[2:3], v[8:9], v[26:27]
	v_cvt_pk_bf16_f32 v0, v0, v1
	s_nop 0
	v_cvt_pk_bf16_f32 v1, v2, v3
	global_store_dwordx2 v[32:33], v[0:1], off offset:256
	global_load_dwordx4 v[0:3], v[132:133], off offset:576
	s_nop 0
	global_load_dwordx4 v[8:11], v[128:129], off offset:576
	global_load_dwordx4 v[16:19], v[130:131], off offset:576
	s_waitcnt lgkmcnt(0)
	v_pk_mul_f32 v[22:23], v[108:109], v[176:177] op_sel_hi:[1,0]
	v_pk_mul_f32 v[20:21], v[110:111], v[176:177] op_sel_hi:[1,0]
	s_waitcnt vmcnt(2)
	v_pk_add_f32 v[2:3], v[2:3], 1.0 op_sel_hi:[1,0]
	v_pk_add_f32 v[0:1], v[0:1], 1.0 op_sel_hi:[1,0]
	s_waitcnt vmcnt(1)
	v_pk_mul_f32 v[2:3], v[10:11], v[2:3]
	v_pk_mul_f32 v[0:1], v[8:9], v[0:1]
	s_waitcnt vmcnt(0)
	v_pk_fma_f32 v[8:9], v[2:3], v[20:21], v[18:19]
	v_pk_fma_f32 v[10:11], v[0:1], v[22:23], v[16:17]
	s_nop 0
	v_cvt_pk_bf16_f32 v10, v10, v11
	v_cvt_pk_bf16_f32 v11, v8, v9
	global_store_dwordx2 v[124:125], v[10:11], off offset:288
	s_waitcnt lgkmcnt(0)
	v_pk_mul_f32 v[10:11], v[92:93], v[178:179] op_sel_hi:[1,0]
	v_pk_mul_f32 v[8:9], v[94:95], v[178:179] op_sel_hi:[1,0]
	v_pk_fma_f32 v[10:11], v[0:1], v[10:11], v[16:17]
	v_pk_fma_f32 v[8:9], v[2:3], v[8:9], v[18:19]
	v_cvt_pk_bf16_f32 v10, v10, v11
	s_nop 0
	v_cvt_pk_bf16_f32 v11, v8, v9
	global_store_dwordx2 v[112:113], v[10:11], off offset:288
	s_waitcnt lgkmcnt(0)
	v_pk_mul_f32 v[10:11], v[76:77], v[180:181] op_sel_hi:[1,0]
	v_pk_mul_f32 v[8:9], v[78:79], v[180:181] op_sel_hi:[1,0]
	v_pk_fma_f32 v[10:11], v[0:1], v[10:11], v[16:17]
	v_pk_fma_f32 v[8:9], v[2:3], v[8:9], v[18:19]
	v_cvt_pk_bf16_f32 v10, v10, v11
	s_nop 0
	v_cvt_pk_bf16_f32 v11, v8, v9
	global_store_dwordx2 v[96:97], v[10:11], off offset:288
	s_waitcnt lgkmcnt(0)
	v_pk_mul_f32 v[10:11], v[64:65], v[182:183] op_sel_hi:[1,0]
	v_pk_mul_f32 v[8:9], v[66:67], v[182:183] op_sel_hi:[1,0]
	v_pk_fma_f32 v[10:11], v[0:1], v[10:11], v[16:17]
	v_pk_fma_f32 v[8:9], v[2:3], v[8:9], v[18:19]
	v_cvt_pk_bf16_f32 v10, v10, v11
	s_nop 0
	v_cvt_pk_bf16_f32 v11, v8, v9
	global_store_dwordx2 v[80:81], v[10:11], off offset:288
	s_waitcnt lgkmcnt(0)
	v_pk_mul_f32 v[10:11], v[44:45], v[184:185] op_sel_hi:[1,0]
	v_pk_mul_f32 v[8:9], v[46:47], v[184:185] op_sel_hi:[1,0]
	v_pk_fma_f32 v[10:11], v[0:1], v[10:11], v[16:17]
	v_pk_fma_f32 v[8:9], v[2:3], v[8:9], v[18:19]
	v_cvt_pk_bf16_f32 v10, v10, v11
	s_nop 0
	v_cvt_pk_bf16_f32 v11, v8, v9
	global_store_dwordx2 v[60:61], v[10:11], off offset:288
	s_waitcnt lgkmcnt(0)
	v_pk_mul_f32 v[10:11], v[28:29], v[186:187] op_sel_hi:[1,0]
	v_pk_mul_f32 v[8:9], v[30:31], v[186:187] op_sel_hi:[1,0]
	v_pk_fma_f32 v[10:11], v[0:1], v[10:11], v[16:17]
	v_pk_fma_f32 v[8:9], v[2:3], v[8:9], v[18:19]
	v_cvt_pk_bf16_f32 v10, v10, v11
	s_nop 0
	v_cvt_pk_bf16_f32 v11, v8, v9
	global_store_dwordx2 v[48:49], v[10:11], off offset:288
	s_waitcnt lgkmcnt(0)
	v_pk_mul_f32 v[10:11], v[12:13], v[188:189] op_sel_hi:[1,0]
	v_pk_mul_f32 v[8:9], v[14:15], v[188:189] op_sel_hi:[1,0]
	v_pk_fma_f32 v[10:11], v[0:1], v[10:11], v[16:17]
	v_pk_fma_f32 v[8:9], v[2:3], v[8:9], v[18:19]
	v_cvt_pk_bf16_f32 v10, v10, v11
	s_nop 0
	v_cvt_pk_bf16_f32 v11, v8, v9
	global_store_dwordx2 v[34:35], v[10:11], off offset:288
	s_waitcnt lgkmcnt(0)
	v_pk_mul_f32 v[6:7], v[6:7], v[190:191] op_sel_hi:[1,0]
	v_pk_mul_f32 v[4:5], v[4:5], v[190:191] op_sel_hi:[1,0]
	v_pk_fma_f32 v[0:1], v[0:1], v[6:7], v[16:17]
	v_pk_fma_f32 v[2:3], v[2:3], v[4:5], v[18:19]
	v_cvt_pk_bf16_f32 v0, v0, v1
	s_nop 0
	v_cvt_pk_bf16_f32 v1, v2, v3
	global_store_dwordx2 v[32:33], v[0:1], off offset:288
